# GEMM tile-loop exit: vmcnt(16) instead of vmcnt(0) - only the prefetched LDS-DMA must land; meta_gemm loads overlap the epilogue store drain
# speedup vs baseline: 1.0003x; 1.0003x over previous
; #define PG8_STAGE(bufoff, gbase, voff) do { _Pragma("unroll") for (int _i = 0; _i < 2; ++_i) \
;         __builtin_amdgcn_global_load_lds((const unsigned*)((const char*)(gbase) + (voff)[_i]), (LAS unsigned*)(lds + (bufoff) + ldsw + _i * 8192), 16, 0, 0); } while (0)
; #define PG8_LDA(dst, b, h) do { _Pragma("unroll") for (int m = 0; m < 4; ++m) _Pragma("unroll") for (int k = 0; k < 2; ++k) dst[m][k] = *(const LAS bf16x8*)(lds + PG8_SA(b, h) + aoff + m * 2048 + k * 1024); } while (0)
; #define PG8_LDB(dst, b, h) do { _Pragma("unroll") for (int n = 0; n < 2; ++n) _Pragma("unroll") for (int k = 0; k < 2; ++k) dst[n][k] = *(const LAS bf16x8*)(lds + PG8_SB(b, h) + boff + n * 2048 + k * 1024); } while (0)
; #define PG8_MMA(ai, bj, At, Bt) do { __builtin_amdgcn_s_setprio(1); _Pragma("unroll") for (int m = 0; m < 4; ++m) _Pragma("unroll") for (int n = 0; n < 2; ++n) _Pragma("unroll") for (int k = 0; k < 2; ++k) \
;         acc[ai][bj][m][n] = __builtin_amdgcn_mfma_f32_16x16x32_bf16(Bt[n][k], At[m][k], acc[ai][bj][m][n], 0, 0, 0); __builtin_amdgcn_s_setprio(0); } while (0)
; #define PG8_WAIT_V(n) asm volatile("s_waitcnt vmcnt(" #n ")" ::: "memory")
; #define PG8_WAIT_L(n) asm volatile("s_waitcnt lgkmcnt(" #n ")" ::: "memory")
; #define PG8_BAR __builtin_amdgcn_s_barrier()
; #define PG8_SCHED __builtin_amdgcn_sched_barrier(0)
; template <class Epi>
; DI void gemm_phase(LAS unsigned char* lds, const Gemm g, const StaticOrder& S, const Epi& E, const int tid) {
;     ...
;             PG8_LDB(B0, 0, 0); PG8_SCHED; PG8_LDA(At, 0, 0); PG8_STAGE(PG8_SA(1, 1), a1 + hstepA, voffA);
;             PG8_WAIT_L(8); PG8_BAR; PG8_WAIT_L(0); PG8_MMA(0, 0, At, B0); PG8_BAR; PG8_SCHED;
;             PG8_LDB(B1, 0, 1); PG8_STAGE(PG8_SB(0, 0), b2, voffB);
;             PG8_BAR; PG8_WAIT_L(0); PG8_MMA(0, 1, At, B1); PG8_BAR;
;             PG8_LDA(At, 0, 1); PG8_STAGE(PG8_SA(0, 0), a2, voffA);
;             PG8_BAR; PG8_WAIT_L(0); PG8_MMA(1, 0, At, B0); PG8_BAR; PG8_SCHED;
;             PG8_STAGE(PG8_SB(0, 1), b2 + hstepB, voffB);
;             PG8_WAIT_V(6); PG8_BAR; PG8_MMA(1, 1, At, B1); PG8_BAR;
.LBB0_62:
	s_add_i32 s69, 0, 0x10000
	ds_read_b128 v[158:161], v241
	ds_read_b128 v[162:165], v241 offset:1024
	ds_read_b128 v[166:169], v241 offset:2048
	ds_read_b128 v[178:181], v241 offset:3072
	s_add_i32 m0, s41, 0xc000
	ds_read_b128 v[182:185], v151
	ds_read_b128 v[186:189], v151 offset:1024
	ds_read_b128 v[190:193], v151 offset:2048
	ds_read_b128 v[194:197], v151 offset:3072
	ds_read_b128 v[198:201], v151 offset:4096
	ds_read_b128 v[202:205], v151 offset:5120
	ds_read_b128 v[206:209], v151 offset:6144
	ds_read_b128 v[210:213], v151 offset:7168
	global_load_lds_dwordx4 v138, s[86:87]
	s_add_i32 m0, s41, 0xe000
	s_nop 0
	global_load_lds_dwordx4 v140, s[86:87]
	s_waitcnt lgkmcnt(8)
	s_barrier
	s_waitcnt lgkmcnt(0)
	s_setprio 1
	s_waitcnt lgkmcnt(0)
	v_mfma_f32_16x16x32_bf16 v[126:129], v[158:161], v[182:185], v[126:129]
	v_mfma_f32_16x16x32_bf16 v[122:125], v[166:169], v[182:185], v[122:125]
	v_mfma_f32_16x16x32_bf16 v[118:121], v[158:161], v[190:193], v[118:121]
	v_mfma_f32_16x16x32_bf16 v[114:117], v[166:169], v[190:193], v[114:117]
	v_mfma_f32_16x16x32_bf16 v[102:105], v[158:161], v[198:201], v[102:105]
	v_mfma_f32_16x16x32_bf16 v[98:101], v[166:169], v[198:201], v[98:101]
	v_mfma_f32_16x16x32_bf16 v[86:89], v[158:161], v[206:209], v[86:89]
	v_mfma_f32_16x16x32_bf16 v[82:85], v[166:169], v[206:209], v[82:85]
	v_mfma_f32_16x16x32_bf16 v[126:129], v[162:165], v[186:189], v[126:129]
	v_mfma_f32_16x16x32_bf16 v[122:125], v[178:181], v[186:189], v[122:125]
	v_mfma_f32_16x16x32_bf16 v[118:121], v[162:165], v[194:197], v[118:121]
	v_mfma_f32_16x16x32_bf16 v[114:117], v[178:181], v[194:197], v[114:117]
	v_mfma_f32_16x16x32_bf16 v[102:105], v[162:165], v[202:205], v[102:105]
	v_mfma_f32_16x16x32_bf16 v[98:101], v[178:181], v[202:205], v[98:101]
	v_mfma_f32_16x16x32_bf16 v[86:89], v[162:165], v[210:213], v[86:89]
	v_mfma_f32_16x16x32_bf16 v[82:85], v[178:181], v[210:213], v[82:85]
	s_setprio 0
	s_barrier
	s_add_i32 s78, 0, 0x14000
	s_add_i32 s69, s69, s26
	ds_read_b128 v[214:217], v242
	ds_read_b128 v[218:221], v242 offset:1024
	ds_read_b128 v[222:225], v242 offset:2048
	ds_read_b128 v[226:229], v242 offset:3072
	s_mov_b32 m0, s69
	s_nop 0
	global_load_lds_dwordx4 v0, s[6:7]
	s_add_i32 m0, s69, 0x2000
	s_nop 0
	global_load_lds_dwordx4 v130, s[6:7]
	s_barrier
	s_waitcnt lgkmcnt(0)
	s_setprio 1
	s_waitcnt lgkmcnt(0)
	v_mfma_f32_16x16x32_bf16 v[110:113], v[214:217], v[182:185], v[110:113]
	v_mfma_f32_16x16x32_bf16 v[106:109], v[222:225], v[182:185], v[106:109]
	v_mfma_f32_16x16x32_bf16 v[94:97], v[214:217], v[190:193], v[94:97]
	v_mfma_f32_16x16x32_bf16 v[90:93], v[222:225], v[190:193], v[90:93]
	v_mfma_f32_16x16x32_bf16 v[78:81], v[214:217], v[198:201], v[78:81]
	v_mfma_f32_16x16x32_bf16 v[74:77], v[222:225], v[198:201], v[74:77]
	v_mfma_f32_16x16x32_bf16 v[70:73], v[214:217], v[206:209], v[70:73]
	v_mfma_f32_16x16x32_bf16 v[66:69], v[222:225], v[206:209], v[66:69]
	v_mfma_f32_16x16x32_bf16 v[110:113], v[218:221], v[186:189], v[110:113]
	v_mfma_f32_16x16x32_bf16 v[106:109], v[226:229], v[186:189], v[106:109]
	v_mfma_f32_16x16x32_bf16 v[94:97], v[218:221], v[194:197], v[94:97]
	v_mfma_f32_16x16x32_bf16 v[90:93], v[226:229], v[194:197], v[90:93]
	v_mfma_f32_16x16x32_bf16 v[78:81], v[218:221], v[202:205], v[78:81]
	v_mfma_f32_16x16x32_bf16 v[74:77], v[226:229], v[202:205], v[74:77]
	v_mfma_f32_16x16x32_bf16 v[70:73], v[218:221], v[210:213], v[70:73]
	v_mfma_f32_16x16x32_bf16 v[66:69], v[226:229], v[210:213], v[66:69]
	s_setprio 0
	s_mov_b32 m0, s41
	s_barrier
	ds_read_b128 v[182:185], v151 offset:16384
	ds_read_b128 v[186:189], v151 offset:17408
	ds_read_b128 v[190:193], v151 offset:18432
	ds_read_b128 v[194:197], v151 offset:19456
	ds_read_b128 v[198:201], v151 offset:20480
	ds_read_b128 v[202:205], v151 offset:21504
	ds_read_b128 v[206:209], v151 offset:22528
	ds_read_b128 v[210:213], v151 offset:23552
	global_load_lds_dwordx4 v134, s[50:51]
	s_mov_b32 m0, s55
	s_nop 0
	global_load_lds_dwordx4 v132, s[50:51]
	s_barrier
	s_waitcnt lgkmcnt(0)
	s_setprio 1
	s_waitcnt lgkmcnt(0)
	v_mfma_f32_16x16x32_bf16 v[62:65], v[158:161], v[182:185], v[62:65]
	v_mfma_f32_16x16x32_bf16 v[58:61], v[166:169], v[182:185], v[58:61]
	v_mfma_f32_16x16x32_bf16 v[54:57], v[158:161], v[190:193], v[54:57]
	v_mfma_f32_16x16x32_bf16 v[50:53], v[166:169], v[190:193], v[50:53]
	v_mfma_f32_16x16x32_bf16 v[38:41], v[158:161], v[198:201], v[38:41]
	v_mfma_f32_16x16x32_bf16 v[34:37], v[166:169], v[198:201], v[34:37]
	v_mfma_f32_16x16x32_bf16 v[22:25], v[158:161], v[206:209], v[22:25]
	v_mfma_f32_16x16x32_bf16 v[18:21], v[166:169], v[206:209], v[18:21]
	v_mfma_f32_16x16x32_bf16 v[62:65], v[162:165], v[186:189], v[62:65]
	v_mfma_f32_16x16x32_bf16 v[58:61], v[178:181], v[186:189], v[58:61]
	v_mfma_f32_16x16x32_bf16 v[54:57], v[162:165], v[194:197], v[54:57]
	v_mfma_f32_16x16x32_bf16 v[50:53], v[178:181], v[194:197], v[50:53]
	v_mfma_f32_16x16x32_bf16 v[38:41], v[162:165], v[202:205], v[38:41]
	v_mfma_f32_16x16x32_bf16 v[34:37], v[178:181], v[202:205], v[34:37]
	v_mfma_f32_16x16x32_bf16 v[22:25], v[162:165], v[210:213], v[22:25]
	v_mfma_f32_16x16x32_bf16 v[18:21], v[178:181], v[210:213], v[18:21]
	s_setprio 0
	s_barrier
	s_add_u32 s86, s6, 0x80000
	s_addc_u32 s87, s7, 0
	s_add_i32 s69, s78, s26
	s_mov_b32 m0, s69
	s_nop 0
	global_load_lds_dwordx4 v0, s[86:87]
	s_add_i32 m0, s69, 0x2000
	s_nop 0
	global_load_lds_dwordx4 v130, s[86:87]
	s_waitcnt vmcnt(6)
	s_barrier
; #define PG8_STAGE(bufoff, gbase, voff) do { _Pragma("unroll") for (int _i = 0; _i < 2; ++_i) \
;         __builtin_amdgcn_global_load_lds((const unsigned*)((const char*)(gbase) + (voff)[_i]), (LAS unsigned*)(lds + (bufoff) + ldsw + _i * 8192), 16, 0, 0); } while (0)
; #define PG8_LDA(dst, b, h) do { _Pragma("unroll") for (int m = 0; m < 4; ++m) _Pragma("unroll") for (int k = 0; k < 2; ++k) dst[m][k] = *(const LAS bf16x8*)(lds + PG8_SA(b, h) + aoff + m * 2048 + k * 1024); } while (0)
; #define PG8_LDB(dst, b, h) do { _Pragma("unroll") for (int n = 0; n < 2; ++n) _Pragma("unroll") for (int k = 0; k < 2; ++k) dst[n][k] = *(const LAS bf16x8*)(lds + PG8_SB(b, h) + boff + n * 2048 + k * 1024); } while (0)
; #define PG8_MMA(ai, bj, At, Bt) do { __builtin_amdgcn_s_setprio(1); _Pragma("unroll") for (int m = 0; m < 4; ++m) _Pragma("unroll") for (int n = 0; n < 2; ++n) _Pragma("unroll") for (int k = 0; k < 2; ++k) \
;         acc[ai][bj][m][n] = __builtin_amdgcn_mfma_f32_16x16x32_bf16(Bt[n][k], At[m][k], acc[ai][bj][m][n], 0, 0, 0); __builtin_amdgcn_s_setprio(0); } while (0)
; #define PG8_WAIT_V(n) asm volatile("s_waitcnt vmcnt(" #n ")" ::: "memory")
; #define PG8_WAIT_L(n) asm volatile("s_waitcnt lgkmcnt(" #n ")" ::: "memory")
; #define PG8_BAR __builtin_amdgcn_s_barrier()
; #define PG8_SCHED __builtin_amdgcn_sched_barrier(0)
; template <class Epi>
; DI void gemm_phase(LAS unsigned char* lds, const Gemm g, const StaticOrder& S, const Epi& E, const int tid) {
;     ...
;             PG8_WAIT_V(6); PG8_BAR; PG8_MMA(1, 1, At, B1); PG8_BAR;
;             PG8_LDB(B0, 1, 0); PG8_SCHED; PG8_LDA(At, 1, 0); PG8_STAGE(PG8_SA(0, 1), a2 + hstepA, voffA);
;             PG8_WAIT_L(8); PG8_BAR; PG8_WAIT_L(0); PG8_MMA(0, 0, At, B0); PG8_BAR; PG8_SCHED;
;             PG8_LDB(B1, 1, 1); PG8_STAGE(PG8_SB(1, 0), b3, voffB);
;             PG8_BAR; PG8_WAIT_L(0); PG8_MMA(0, 1, At, B1); PG8_BAR;
;             PG8_LDA(At, 1, 1); PG8_STAGE(PG8_SA(1, 0), a3, voffA);
	s_setprio 1
	v_mfma_f32_16x16x32_bf16 v[46:49], v[214:217], v[182:185], v[46:49]
	v_mfma_f32_16x16x32_bf16 v[42:45], v[222:225], v[182:185], v[42:45]
	v_mfma_f32_16x16x32_bf16 v[30:33], v[214:217], v[190:193], v[30:33]
	v_mfma_f32_16x16x32_bf16 v[26:29], v[222:225], v[190:193], v[26:29]
	v_mfma_f32_16x16x32_bf16 v[14:17], v[214:217], v[198:201], v[14:17]
	v_mfma_f32_16x16x32_bf16 v[10:13], v[222:225], v[198:201], v[10:13]
	v_mfma_f32_16x16x32_bf16 v[6:9], v[214:217], v[206:209], v[6:9]
	v_mfma_f32_16x16x32_bf16 v[2:5], v[222:225], v[206:209], v[2:5]
	v_mfma_f32_16x16x32_bf16 v[46:49], v[218:221], v[186:189], v[46:49]
	v_mfma_f32_16x16x32_bf16 v[42:45], v[226:229], v[186:189], v[42:45]
	v_mfma_f32_16x16x32_bf16 v[30:33], v[218:221], v[194:197], v[30:33]
	v_mfma_f32_16x16x32_bf16 v[26:29], v[226:229], v[194:197], v[26:29]
	v_mfma_f32_16x16x32_bf16 v[14:17], v[218:221], v[202:205], v[14:17]
	v_mfma_f32_16x16x32_bf16 v[10:13], v[226:229], v[202:205], v[10:13]
	v_mfma_f32_16x16x32_bf16 v[6:9], v[218:221], v[210:213], v[6:9]
	v_mfma_f32_16x16x32_bf16 v[2:5], v[226:229], v[210:213], v[2:5]
	s_setprio 0
	s_add_i32 s69, 0, 0x18000
	s_barrier
	ds_read_b128 v[158:161], v243
	ds_read_b128 v[162:165], v243 offset:1024
	ds_read_b128 v[166:169], v243 offset:2048
	ds_read_b128 v[178:181], v243 offset:3072
	s_add_u32 s50, s50, 0x80000
	s_addc_u32 s51, s51, 0
	s_mov_b32 m0, s56
	s_nop 0
	ds_read_b128 v[182:185], v151 offset:32768
	ds_read_b128 v[186:189], v151 offset:33792
	ds_read_b128 v[190:193], v151 offset:34816
	ds_read_b128 v[194:197], v151 offset:35840
	ds_read_b128 v[198:201], v151 offset:36864
	ds_read_b128 v[202:205], v151 offset:37888
	ds_read_b128 v[206:209], v151 offset:38912
	ds_read_b128 v[210:213], v151 offset:39936
	global_load_lds_dwordx4 v134, s[50:51]
	s_mov_b32 m0, s57
	s_nop 0
	global_load_lds_dwordx4 v132, s[50:51]
	s_waitcnt lgkmcnt(8)
	s_barrier
	s_waitcnt lgkmcnt(0)
	s_setprio 1
	s_waitcnt lgkmcnt(0)
	v_mfma_f32_16x16x32_bf16 v[126:129], v[158:161], v[182:185], v[126:129]
	v_mfma_f32_16x16x32_bf16 v[122:125], v[166:169], v[182:185], v[122:125]
	v_mfma_f32_16x16x32_bf16 v[118:121], v[158:161], v[190:193], v[118:121]
	v_mfma_f32_16x16x32_bf16 v[114:117], v[166:169], v[190:193], v[114:117]
	v_mfma_f32_16x16x32_bf16 v[102:105], v[158:161], v[198:201], v[102:105]
	v_mfma_f32_16x16x32_bf16 v[98:101], v[166:169], v[198:201], v[98:101]
	v_mfma_f32_16x16x32_bf16 v[86:89], v[158:161], v[206:209], v[86:89]
	v_mfma_f32_16x16x32_bf16 v[82:85], v[166:169], v[206:209], v[82:85]
	v_mfma_f32_16x16x32_bf16 v[126:129], v[162:165], v[186:189], v[126:129]
	v_mfma_f32_16x16x32_bf16 v[122:125], v[178:181], v[186:189], v[122:125]
	v_mfma_f32_16x16x32_bf16 v[118:121], v[162:165], v[194:197], v[118:121]
	v_mfma_f32_16x16x32_bf16 v[114:117], v[178:181], v[194:197], v[114:117]
	v_mfma_f32_16x16x32_bf16 v[102:105], v[162:165], v[202:205], v[102:105]
	v_mfma_f32_16x16x32_bf16 v[98:101], v[178:181], v[202:205], v[98:101]
	v_mfma_f32_16x16x32_bf16 v[86:89], v[162:165], v[210:213], v[86:89]
	v_mfma_f32_16x16x32_bf16 v[82:85], v[178:181], v[210:213], v[82:85]
	s_setprio 0
	s_barrier
	s_add_i32 s50, 0, 0x1c000
	s_add_i32 s51, s69, s26
	s_add_u32 s86, s6, s84
	s_addc_u32 s87, s7, s85
	s_mov_b32 m0, s51
	ds_read_b128 v[214:217], v244
	ds_read_b128 v[218:221], v244 offset:1024
	ds_read_b128 v[222:225], v244 offset:2048
	ds_read_b128 v[226:229], v244 offset:3072
	global_load_lds_dwordx4 v0, s[86:87]
	s_add_i32 m0, s51, 0x2000
	s_nop 0
	global_load_lds_dwordx4 v130, s[86:87]
	s_barrier
	s_waitcnt lgkmcnt(0)
	s_setprio 1
	s_waitcnt lgkmcnt(0)
	v_mfma_f32_16x16x32_bf16 v[110:113], v[214:217], v[182:185], v[110:113]
	v_mfma_f32_16x16x32_bf16 v[106:109], v[222:225], v[182:185], v[106:109]
	v_mfma_f32_16x16x32_bf16 v[94:97], v[214:217], v[190:193], v[94:97]
	v_mfma_f32_16x16x32_bf16 v[90:93], v[222:225], v[190:193], v[90:93]
	v_mfma_f32_16x16x32_bf16 v[78:81], v[214:217], v[198:201], v[78:81]
	v_mfma_f32_16x16x32_bf16 v[74:77], v[222:225], v[198:201], v[74:77]
	v_mfma_f32_16x16x32_bf16 v[70:73], v[214:217], v[206:209], v[70:73]
	v_mfma_f32_16x16x32_bf16 v[66:69], v[222:225], v[206:209], v[66:69]
	v_mfma_f32_16x16x32_bf16 v[110:113], v[218:221], v[186:189], v[110:113]
	v_mfma_f32_16x16x32_bf16 v[106:109], v[226:229], v[186:189], v[106:109]
	v_mfma_f32_16x16x32_bf16 v[94:97], v[218:221], v[194:197], v[94:97]
	v_mfma_f32_16x16x32_bf16 v[90:93], v[226:229], v[194:197], v[90:93]
	v_mfma_f32_16x16x32_bf16 v[78:81], v[218:221], v[202:205], v[78:81]
	v_mfma_f32_16x16x32_bf16 v[74:77], v[226:229], v[202:205], v[74:77]
	v_mfma_f32_16x16x32_bf16 v[70:73], v[218:221], v[210:213], v[70:73]
	v_mfma_f32_16x16x32_bf16 v[66:69], v[226:229], v[210:213], v[66:69]
	s_setprio 0
	s_mov_b32 m0, s59
	s_nop 0
	s_barrier
	ds_read_b128 v[182:185], v151 offset:49152
	ds_read_b128 v[186:189], v151 offset:50176
	ds_read_b128 v[190:193], v151 offset:51200
	ds_read_b128 v[194:197], v151 offset:52224
	ds_read_b128 v[198:201], v151 offset:53248
	ds_read_b128 v[202:205], v151 offset:54272
	ds_read_b128 v[206:209], v151 offset:55296
	ds_read_b128 v[210:213], v151 offset:56320
	global_load_lds_dwordx4 v134, s[8:9]
	s_mov_b32 m0, s60
	s_nop 0
	global_load_lds_dwordx4 v132, s[8:9]
	s_barrier
; #define PG8_STAGE(bufoff, gbase, voff) do { _Pragma("unroll") for (int _i = 0; _i < 2; ++_i) \
;         __builtin_amdgcn_global_load_lds((const unsigned*)((const char*)(gbase) + (voff)[_i]), (LAS unsigned*)(lds + (bufoff) + ldsw + _i * 8192), 16, 0, 0); } while (0)
; #define PG8_LDA(dst, b, h) do { _Pragma("unroll") for (int m = 0; m < 4; ++m) _Pragma("unroll") for (int k = 0; k < 2; ++k) dst[m][k] = *(const LAS bf16x8*)(lds + PG8_SA(b, h) + aoff + m * 2048 + k * 1024); } while (0)
; #define PG8_MMA(ai, bj, At, Bt) do { __builtin_amdgcn_s_setprio(1); _Pragma("unroll") for (int m = 0; m < 4; ++m) _Pragma("unroll") for (int n = 0; n < 2; ++n) _Pragma("unroll") for (int k = 0; k < 2; ++k) \
;         acc[ai][bj][m][n] = __builtin_amdgcn_mfma_f32_16x16x32_bf16(Bt[n][k], At[m][k], acc[ai][bj][m][n], 0, 0, 0); __builtin_amdgcn_s_setprio(0); } while (0)
; #define PG8_WAIT_V(n) asm volatile("s_waitcnt vmcnt(" #n ")" ::: "memory")
; #define PG8_WAIT_L(n) asm volatile("s_waitcnt lgkmcnt(" #n ")" ::: "memory")
; #define PG8_BAR __builtin_amdgcn_s_barrier()
; #define PG8_SCHED __builtin_amdgcn_sched_barrier(0)
; template <class Epi>
; DI void gemm_phase(LAS unsigned char* lds, const Gemm g, const StaticOrder& S, const Epi& E, const int tid) {
;     ...
;         for (int t = 0; t < nt; t += 2) {
;             const bool last = (t == nt - 2);
;             const char* a1 = cA + PG8_KTA(t + 1);
;             const char* a2 = last ? nA : cA + PG8_KTA(t + 2); const char* b2 = last ? nB : cB + (size_t)(t + 2) * kstep;
;             const char* a3 = last ? nA + PG8_KTA(1) : cA + PG8_KTA(t + 3); const char* b3 = b2 + kstep;
;     ...
;             PG8_BAR; PG8_WAIT_L(0); PG8_MMA(0, 1, At, B1); PG8_BAR;
;             PG8_LDA(At, 1, 1); PG8_STAGE(PG8_SA(1, 0), a3, voffA);
;             PG8_BAR; PG8_WAIT_L(0); PG8_MMA(1, 0, At, B0); PG8_BAR; PG8_SCHED;
;             PG8_STAGE(PG8_SB(1, 1), b3 + hstepB, voffB);
;             PG8_WAIT_V(6); PG8_BAR; PG8_MMA(1, 1, At, B1); PG8_BAR;
	s_waitcnt lgkmcnt(0)
	s_setprio 1
	s_waitcnt lgkmcnt(0)
	v_mfma_f32_16x16x32_bf16 v[62:65], v[158:161], v[182:185], v[62:65]
	v_mfma_f32_16x16x32_bf16 v[58:61], v[166:169], v[182:185], v[58:61]
	v_mfma_f32_16x16x32_bf16 v[54:57], v[158:161], v[190:193], v[54:57]
	v_mfma_f32_16x16x32_bf16 v[50:53], v[166:169], v[190:193], v[50:53]
	v_mfma_f32_16x16x32_bf16 v[38:41], v[158:161], v[198:201], v[38:41]
	v_mfma_f32_16x16x32_bf16 v[34:37], v[166:169], v[198:201], v[34:37]
	v_mfma_f32_16x16x32_bf16 v[22:25], v[158:161], v[206:209], v[22:25]
	v_mfma_f32_16x16x32_bf16 v[18:21], v[166:169], v[206:209], v[18:21]
	v_mfma_f32_16x16x32_bf16 v[62:65], v[162:165], v[186:189], v[62:65]
	v_mfma_f32_16x16x32_bf16 v[58:61], v[178:181], v[186:189], v[58:61]
	v_mfma_f32_16x16x32_bf16 v[54:57], v[162:165], v[194:197], v[54:57]
	v_mfma_f32_16x16x32_bf16 v[50:53], v[178:181], v[194:197], v[50:53]
	v_mfma_f32_16x16x32_bf16 v[38:41], v[162:165], v[202:205], v[38:41]
	v_mfma_f32_16x16x32_bf16 v[34:37], v[178:181], v[202:205], v[34:37]
	v_mfma_f32_16x16x32_bf16 v[22:25], v[162:165], v[210:213], v[22:25]
	v_mfma_f32_16x16x32_bf16 v[18:21], v[178:181], v[210:213], v[18:21]
	s_setprio 0
	s_barrier
	s_add_u32 s6, s6, 0x80080
	s_addc_u32 s7, s7, 0
	s_add_i32 s8, s50, s26
	s_mov_b32 m0, s8
	s_nop 0
	global_load_lds_dwordx4 v0, s[6:7]
	s_add_i32 m0, s8, 0x2000
	s_nop 0
	global_load_lds_dwordx4 v130, s[6:7]
	s_waitcnt vmcnt(6)
	s_barrier
	s_setprio 1
	v_mfma_f32_16x16x32_bf16 v[46:49], v[214:217], v[182:185], v[46:49]
	v_mfma_f32_16x16x32_bf16 v[42:45], v[222:225], v[182:185], v[42:45]
	v_mfma_f32_16x16x32_bf16 v[30:33], v[214:217], v[190:193], v[30:33]
	v_mfma_f32_16x16x32_bf16 v[26:29], v[222:225], v[190:193], v[26:29]
	v_mfma_f32_16x16x32_bf16 v[14:17], v[214:217], v[198:201], v[14:17]
	v_mfma_f32_16x16x32_bf16 v[10:13], v[222:225], v[198:201], v[10:13]
	v_mfma_f32_16x16x32_bf16 v[6:9], v[214:217], v[206:209], v[6:9]
	v_mfma_f32_16x16x32_bf16 v[2:5], v[222:225], v[206:209], v[2:5]
	v_mfma_f32_16x16x32_bf16 v[46:49], v[218:221], v[186:189], v[46:49]
	v_mfma_f32_16x16x32_bf16 v[42:45], v[226:229], v[186:189], v[42:45]
	v_mfma_f32_16x16x32_bf16 v[30:33], v[218:221], v[194:197], v[30:33]
	v_mfma_f32_16x16x32_bf16 v[26:29], v[226:229], v[194:197], v[26:29]
	v_mfma_f32_16x16x32_bf16 v[14:17], v[218:221], v[202:205], v[14:17]
	v_mfma_f32_16x16x32_bf16 v[10:13], v[226:229], v[202:205], v[10:13]
	v_mfma_f32_16x16x32_bf16 v[6:9], v[218:221], v[210:213], v[6:9]
	v_mfma_f32_16x16x32_bf16 v[2:5], v[226:229], v[210:213], v[2:5]
	s_setprio 0
	s_add_i32 s68, s68, 2
	s_add_u32 s4, s4, 0x100
	s_addc_u32 s5, s5, 0
	s_add_u32 s6, s44, s4
	s_addc_u32 s7, s45, s5
	s_add_u32 s8, s6, 0x100
	s_addc_u32 s9, s7, 0
	s_add_u32 s69, s66, s4
	s_addc_u32 s78, s67, s5
	s_add_u32 s86, s6, 0x180
	s_addc_u32 s87, s7, 0
	s_cmpk_eq_i32 s4, 0xf00
	s_cselect_b32 s51, s30, s9
	s_cselect_b32 s50, s31, s8
	s_cselect_b32 s7, s39, s78
	s_cselect_b32 s6, s43, s69
	s_cselect_b32 s9, s65, s87
	s_cselect_b32 s8, s64, s86
	s_add_u32 s86, s44, s4
	s_addc_u32 s87, s45, s5
	s_add_u32 s86, s86, 0x80080
	s_addc_u32 s87, s87, 0
	s_cmp_gt_u32 s68, 29
	s_barrier
	s_cbranch_scc0 .LBB0_62
; DI unsigned pk2(float a, float b) { f32x2 v = {a, b}; bf16v2 r = __builtin_convertvector(v, bf16v2); return __builtin_bit_cast(unsigned, r); }
; #define PG8_WAIT_V(n) asm volatile("s_waitcnt vmcnt(" #n ")" ::: "memory")
; #define PG8_BAR __builtin_amdgcn_s_barrier()
;     DI void operator()(const f32x4 (&acc)[2][2][4][2], const Unit& u, int wr, int wc, int fr, int fq) const {
;     ...
;             unsigned char* tb = (unsigned char*)O + ((size_t)(u.pm * nt + u.pn) << 17) + (wr * 4 + wc) * 1024 + (fq * 16 + fr) * 16;
; #pragma unroll
;             for (int ai = 0; ai < 2; ++ai)
; #pragma unroll
;                 for (int m = 0; m < 4; ++m)
; #pragma unroll
;                     for (int bj = 0; bj < 2; ++bj) { const f32x4 v0 = acc[ai][bj][m][0], v1 = acc[ai][bj][m][1];
;                         u32x4 w; w.x = pk2(v0[0], v0[1]); w.y = pk2(v0[2], v0[3]); w.z = pk2(v1[0], v1[1]); w.w = pk2(v1[2], v1[3]);
;                         *(u32x4*)(tb + ((ai * 4 + m) * 2 + bj) * 8192) = w; }
; template <class Epi>
; DI void gemm_phase(LAS unsigned char* lds, const Gemm g, const StaticOrder& S, const Epi& E, const int tid) {
;     ...
;     PG8_WAIT_V(0);
;     if (wr == 0) PG8_BAR;
	s_mul_i32 s4, s40, s58
	s_add_i32 s4, s4, s63
	s_ashr_i32 s5, s4, 31
	s_lshl_b64 s[4:5], s[4:5], 17
	v_lshl_add_u64 v[144:145], v[136:137], 0, s[4:5]
	s_movk_i32 s4, 0x2000
	v_cvt_pk_bf16_f32 v110, v110, v111
	v_cvt_pk_bf16_f32 v111, v112, v113
	v_cvt_pk_bf16_f32 v112, v106, v107
	v_add_co_u32_e32 v106, vcc, s4, v144
	v_cvt_pk_bf16_f32 v113, v108, v109
	s_nop 0
	v_addc_co_u32_e32 v107, vcc, 0, v145, vcc
	global_store_dwordx4 v[106:107], v[110:113], off
	s_movk_i32 s4, 0x6000
	v_cvt_pk_bf16_f32 v94, v94, v95
	v_add_co_u32_e32 v110, vcc, s3, v144
	v_cvt_pk_bf16_f32 v95, v96, v97
	s_nop 0
	v_addc_co_u32_e32 v111, vcc, 0, v145, vcc
	v_cvt_pk_bf16_f32 v96, v90, v91
	v_add_co_u32_e32 v90, vcc, s4, v144
	v_cvt_pk_bf16_f32 v97, v92, v93
	s_nop 0
	v_addc_co_u32_e32 v91, vcc, 0, v145, vcc
	s_mov_b32 s4, 0x8000
	global_store_dwordx4 v[90:91], v[94:97], off
	v_cvt_pk_bf16_f32 v78, v78, v79
	v_cvt_pk_bf16_f32 v79, v80, v81
	v_add_co_u32_e32 v94, vcc, s4, v144
	s_mov_b32 s4, 0xa000
	s_nop 0
	v_addc_co_u32_e32 v95, vcc, 0, v145, vcc
	v_cvt_pk_bf16_f32 v80, v74, v75
	v_add_co_u32_e32 v74, vcc, s4, v144
	v_cvt_pk_bf16_f32 v81, v76, v77
	s_nop 0
	v_addc_co_u32_e32 v75, vcc, 0, v145, vcc
	global_store_dwordx4 v[74:75], v[78:81], off
	s_mov_b32 s4, 0xe000
	v_cvt_pk_bf16_f32 v70, v70, v71
	v_add_co_u32_e32 v78, vcc, s13, v144
	v_cvt_pk_bf16_f32 v71, v72, v73
	s_nop 0
	v_addc_co_u32_e32 v79, vcc, 0, v145, vcc
	v_cvt_pk_bf16_f32 v72, v66, v67
	v_add_co_u32_e32 v66, vcc, s4, v144
	s_mov_b32 s4, 0x10000
	s_nop 0
	v_addc_co_u32_e32 v67, vcc, 0, v145, vcc
	v_cvt_pk_bf16_f32 v62, v62, v63
	v_cvt_pk_bf16_f32 v63, v64, v65
	v_cvt_pk_bf16_f32 v64, v58, v59
	v_add_co_u32_e32 v58, vcc, s4, v144
	s_mov_b32 s4, 0x12000
	s_nop 0
	v_addc_co_u32_e32 v59, vcc, 0, v145, vcc
	v_cvt_pk_bf16_f32 v46, v46, v47
	v_cvt_pk_bf16_f32 v47, v48, v49
	v_cvt_pk_bf16_f32 v48, v42, v43
	v_add_co_u32_e32 v42, vcc, s4, v144
	v_cvt_pk_bf16_f32 v49, v44, v45
	s_nop 0
	v_addc_co_u32_e32 v43, vcc, 0, v145, vcc
	s_mov_b32 s4, 0x14000
	global_store_dwordx4 v[42:43], v[46:49], off
	v_cvt_pk_bf16_f32 v30, v30, v31
	v_cvt_pk_bf16_f32 v31, v32, v33
	v_add_co_u32_e32 v46, vcc, s4, v144
	s_mov_b32 s4, 0x16000
	s_nop 0
	v_addc_co_u32_e32 v47, vcc, 0, v145, vcc
	v_cvt_pk_bf16_f32 v32, v26, v27
	v_add_co_u32_e32 v26, vcc, s4, v144
	v_cvt_pk_bf16_f32 v33, v28, v29
	s_nop 0
	v_addc_co_u32_e32 v27, vcc, 0, v145, vcc
	s_mov_b32 s4, 0x18000
	global_store_dwordx4 v[26:27], v[30:33], off
	v_cvt_pk_bf16_f32 v14, v14, v15
	v_cvt_pk_bf16_f32 v15, v16, v17
	v_add_co_u32_e32 v30, vcc, s4, v144
	s_mov_b32 s4, 0x1a000
	s_nop 0
	v_addc_co_u32_e32 v31, vcc, 0, v145, vcc
	v_cvt_pk_bf16_f32 v16, v10, v11
	v_add_co_u32_e32 v10, vcc, s4, v144
	v_cvt_pk_bf16_f32 v17, v12, v13
	s_nop 0
	v_addc_co_u32_e32 v11, vcc, 0, v145, vcc
	s_mov_b32 s4, 0x1c000
	global_store_dwordx4 v[10:11], v[14:17], off
	v_cvt_pk_bf16_f32 v6, v6, v7
	v_cvt_pk_bf16_f32 v7, v8, v9
	v_add_co_u32_e32 v14, vcc, s4, v144
	v_cvt_pk_bf16_f32 v8, v2, v3
	s_nop 0
	v_addc_co_u32_e32 v15, vcc, 0, v145, vcc
	v_add_co_u32_e32 v2, vcc, 0x1e000, v144
	v_cvt_pk_bf16_f32 v126, v126, v127
	s_nop 0
	v_addc_co_u32_e32 v3, vcc, 0, v145, vcc
	v_cvt_pk_bf16_f32 v127, v128, v129
	v_cvt_pk_bf16_f32 v128, v122, v123
	v_cvt_pk_bf16_f32 v129, v124, v125
	v_cvt_pk_bf16_f32 v106, v118, v119
	v_cvt_pk_bf16_f32 v107, v120, v121
	v_cvt_pk_bf16_f32 v108, v114, v115
	v_cvt_pk_bf16_f32 v109, v116, v117
	v_cvt_pk_bf16_f32 v90, v102, v103
	v_cvt_pk_bf16_f32 v91, v104, v105
	v_cvt_pk_bf16_f32 v92, v98, v99
	v_cvt_pk_bf16_f32 v93, v100, v101
	v_cvt_pk_bf16_f32 v74, v86, v87
	v_cvt_pk_bf16_f32 v75, v88, v89
	v_cvt_pk_bf16_f32 v76, v82, v83
	v_cvt_pk_bf16_f32 v77, v84, v85
	v_cvt_pk_bf16_f32 v73, v68, v69
	v_cvt_pk_bf16_f32 v65, v60, v61
	v_cvt_pk_bf16_f32 v42, v54, v55
	v_cvt_pk_bf16_f32 v43, v56, v57
	v_cvt_pk_bf16_f32 v44, v50, v51
	v_cvt_pk_bf16_f32 v45, v52, v53
	v_cvt_pk_bf16_f32 v26, v38, v39
	v_cvt_pk_bf16_f32 v27, v40, v41
	v_cvt_pk_bf16_f32 v28, v34, v35
	v_cvt_pk_bf16_f32 v29, v36, v37
	v_cvt_pk_bf16_f32 v10, v22, v23
	v_cvt_pk_bf16_f32 v11, v24, v25
	v_cvt_pk_bf16_f32 v12, v18, v19
	v_cvt_pk_bf16_f32 v13, v20, v21
	v_cvt_pk_bf16_f32 v9, v4, v5
	s_and_b64 vcc, exec, s[34:35]
	s_mov_b32 s63, s38
	s_mov_b32 s40, s42
	s_mov_b64 s[4:5], s[48:49]
	s_mov_b64 s[44:45], s[46:47]
	global_store_dwordx4 v[144:145], v[126:129], off
	global_store_dwordx4 v[110:111], v[106:109], off
	global_store_dwordx4 v[94:95], v[90:93], off
	global_store_dwordx4 v[78:79], v[74:77], off
	global_store_dwordx4 v[66:67], v[70:73], off
	global_store_dwordx4 v[58:59], v[62:65], off
	global_store_dwordx4 v[46:47], v[42:45], off
	global_store_dwordx4 v[30:31], v[26:29], off
	global_store_dwordx4 v[14:15], v[10:13], off
	global_store_dwordx4 v[2:3], v[6:9], off
	s_cbranch_vccz .LBB0_59
	s_waitcnt vmcnt(16)
	s_cmpk_gt_u32 s25, 0xff
	s_cbranch_scc1 .LBB0_66
	s_barrier

; #define LAS __attribute__((address_space(3)))
; DI size_t zrowU(int row0, int NT) { return ((size_t)((row0 >> 8) * NT) << 16) + (size_t)((((row0 >> 7) & 1) << 15) | (((row0 >> 5) & 1) << 14) | (((row0 >> 6) & 1) << 11)); }
; DI unsigned zlaneRC(int r5, int col) { return (unsigned)(((col >> 8) << 16) | ((r5 >> 4) << 13) | (((col >> 7) & 1) << 12) | (((col >> 5) & 3) << 9) | (((col >> 3) & 3) << 7) | ((r5 & 15) << 3) | (col & 7)); }
; template <bool TILED_IN>
; DI void meta_gemm(const bf16_t* am, int lda, const bf16_t* Wt, int N, bf16_t* zo, int ldzo, int nt, LAS unsigned char* lds, int bid, int G, int wave, int lane) {
;     const int ntasks = N / 16, r = lane & 15, q = lane >> 4, kq = wave & 3;
;     LAS f32x4* part = (LAS f32x4*)lds;
;     for (int t0 = 2 * (G - 1 - bid); t0 < ntasks; t0 += 2 * G) {
;         const int task = t0 + (wave >> 2), n0 = task * 16;
;         const bf16_t* ap = Wt + (size_t)(n0 + r) * D + 8 * q + 512 * kq;
;         const bf16_t* bp = TILED_IN ? am + zrowU(SEQ, nt) + zlaneRC(r, 512 * kq + 8 * q) : am + (size_t)r * lda + 8 * q + 512 * kq;
.LBB0_67:
	s_not_b32 s4, s11
	s_add_i32 s4, s10, s4
	s_lshr_b32 s25, s24, 4
	s_lshl_b32 s4, s4, 1
	s_cmp_ge_i32 s4, s25
	s_cbranch_scc1 .LBB0_74
	s_waitcnt vmcnt(16)
	v_ashrrev_i32_e32 v10, 4, v148
	v_lshlrev_b32_e32 v2, 3, v10
	s_and_b32 s4, s23, 3
	v_ashrrev_i32_e32 v3, 31, v2
	s_lshl_b32 s5, s23, 10
	s_ashr_i32 s26, s23, 2
	v_lshlrev_b64 v[2:3], 1, v[2:3]
	s_lshl_b32 s78, s4, 10
	v_readlane_b32 s6, v239, 2
	s_add_i32 s5, s5, 0
	v_lshl_add_u64 v[4:5], s[36:37], 0, v[2:3]
	v_lshlrev_b32_e32 v0, 12, v149
	v_readlane_b32 s7, v239, 3
	s_cmp_lg_u32 s4, 0
	v_lshl_add_u64 v[6:7], v[4:5], 0, s[78:79]
	v_lshl_add_u64 v[4:5], s[6:7], 0, v[0:1]
	v_lshl_add_u32 v12, v148, 4, s5
	s_cselect_b64 s[4:5], -1, 0
	s_lshl_b32 s6, s24, 15
	s_add_u32 s6, s82, s6
	s_addc_u32 s7, s83, 0
	s_lshl_b32 s23, s10, 1
	s_lshl_b32 s8, s11, 1
	s_sub_i32 s8, s23, s8
	s_add_i32 s24, s8, -2
	s_lshl_b32 s27, s10, 5
	s_lshl_b32 s8, s26, 4
	v_lshl_add_u64 v[2:3], v[4:5], 0, v[2:3]
	s_add_i32 s8, s27, s8
	v_lshl_add_u64 v[8:9], v[2:3], 0, s[78:79]
	v_lshlrev_b32_e32 v0, 2, v10
	v_lshlrev_b32_e32 v2, 3, v149
	s_sub_i32 s8, s8, 32
	v_and_or_b32 v13, v0, 4, v2
	v_add_u32_e32 v0, s8, v0
	s_lshl_b32 s9, s11, 5
	v_subrev_u32_e32 v0, s9, v0
	v_lshlrev_b32_e32 v14, 4, v0
	v_lshlrev_b32_e32 v15, 5, v0
	v_lshlrev_b32_e32 v16, 8, v0
	v_or_b32_e32 v0, s8, v149
	s_lshl_b32 s11, s10, 9
	s_lshl_b32 s28, s10, 10
	s_lshl_b32 s10, s10, 13
	v_subrev_u32_e32 v10, s9, v0
	s_branch .LBB0_70

; #define PG8_WAIT_V(n) asm volatile("s_waitcnt vmcnt(" #n ")" ::: "memory")
; #define PG8_BAR __builtin_amdgcn_s_barrier()
; template <class Epi>
; DI void gemm_phase(LAS unsigned char* lds, const Gemm g, const StaticOrder& S, const Epi& E, const int tid) {
;     ...
;     PG8_WAIT_V(0);
;     if (wr == 0) PG8_BAR;
;     PG8_BAR;
.LBB0_289:
	s_waitcnt vmcnt(16)
	s_cmpk_gt_u32 s24, 0xff
	s_cbranch_scc1 .LBB0_291
	s_barrier
